# scan: LDS waits coalesced (one s_waitcnt covers all loads issued at least 24 instructions earlier)
# baseline (speedup 1.0000x reference)
.LBB0_672:
	s_add_i32 s22, s65, 1
	s_and_b32 s23, s65, 1
	s_mov_b32 s24, 0
	v_and_b32_e32 v224, 63, v64
	v_and_b32_e32 v233, 15, v224
	v_lshrrev_b32_e32 v234, 4, v224
	s_mov_b32 s98, 0
	s_mov_b32 s99, -1
	v_mov_b32_e32 v235, 0
	s_cmp_lg_u32 s65, 0
	s_cbranch_scc1 .Lmy_f_main
	s_bfe_u32 s96, s62, 0x20006
	s_lshl_b32 s100, s96, 11
	v_lshl_add_u32 v72, v224, 2, s100
	s_mul_i32 s97, s96, 0x2700
	s_cmp_gt_u32 s96, 1
	s_cselect_b32 s101, 0x1300, 0
	s_add_i32 s97, s97, s101
	s_add_i32 s97, s97, 0x1c000
	ds_read_b32 v80, v72
	ds_read_b32 v81, v72 offset:256
	ds_read_b32 v82, v72 offset:512
	ds_read_b32 v83, v72 offset:768
	ds_read_b32 v84, v72 offset:1024
	ds_read_b32 v85, v72 offset:1280
	ds_read_b32 v86, v72 offset:1536
	ds_read_b32 v87, v72 offset:1792
	s_cmpk_ge_u32 s62, 0x100
	s_cbranch_scc1 .Lmy_ck_drB_a
	ds_read_b32 v88, v72 offset:8192
	ds_read_b32 v89, v72 offset:8448
	ds_read_b32 v90, v72 offset:8704
	ds_read_b32 v91, v72 offset:8960
	ds_read_b32 v92, v72 offset:9216
	ds_read_b32 v93, v72 offset:9472
	ds_read_b32 v94, v72 offset:9728
	ds_read_b32 v95, v72 offset:9984
	ds_read_b32 v96, v72 offset:32768
	ds_read_b32 v97, v72 offset:33024
	ds_read_b32 v98, v72 offset:33280
	ds_read_b32 v99, v72 offset:33536
	ds_read_b32 v100, v72 offset:33792
	ds_read_b32 v101, v72 offset:34048
	ds_read_b32 v102, v72 offset:34304
	ds_read_b32 v103, v72 offset:34560
	v_and_b32_e32 v74, 3, v224
	v_bfe_u32 v75, v224, 2, 2
	v_lshrrev_b32_e32 v76, 4, v224
	v_lshlrev_b32_e32 v74, 2, v74
	v_lshl_add_u32 v74, v75, 8, v74
	v_lshl_add_u32 v74, v76, 10, v74
	s_add_i32 s100, s97, 0x0
	v_add_u32_e32 v74, s100, v74
	v_xor_b32_e32 v76, 0, v75
	v_xor_b32_e32 v77, 1, v75
	v_xor_b32_e32 v78, 2, v75
	v_xor_b32_e32 v79, 3, v75
	v_lshl_add_u32 v76, v76, 4, v74
	v_lshl_add_u32 v77, v77, 4, v74
	v_lshl_add_u32 v78, v78, 4, v74
	v_lshl_add_u32 v79, v79, 4, v74
	s_waitcnt lgkmcnt(7)
	v_mov_b32_e32 v104, v80
	v_mul_f32_e32 v105, v104, v81
	v_mul_f32_e32 v106, v105, v82
	v_mul_f32_e32 v107, v106, v83
	v_mul_f32_e32 v108, v107, v84
	v_mul_f32_e32 v109, v108, v85
	v_mul_f32_e32 v110, v109, v86
	v_mul_f32_e32 v111, v110, v87
	v_mov_b32_e32 v112, v88
	v_mul_f32_e32 v113, v104, v89
	v_mul_f32_e32 v114, v105, v90
	v_mul_f32_e32 v115, v106, v91
	v_mul_f32_e32 v116, v107, v92
	v_mul_f32_e32 v117, v108, v93
	v_mul_f32_e32 v118, v109, v94
	v_mul_f32_e32 v119, v110, v95
	v_mul_f32_e32 v120, v104, v96
	s_waitcnt lgkmcnt(0)
	v_mul_f32_e32 v121, v105, v97
	v_mul_f32_e32 v122, v106, v98
	v_mul_f32_e32 v123, v107, v99
	v_mul_f32_e32 v124, v108, v100
	v_mul_f32_e32 v125, v109, v101
	v_mul_f32_e32 v126, v110, v102
	v_mul_f32_e32 v127, v111, v103
	ds_write_b32 v76, v112
	ds_write_b32 v77, v113
	ds_write_b32 v78, v114
	ds_write_b32 v79, v115
	ds_write_b32 v76, v116 offset:64
	ds_write_b32 v77, v117 offset:64
	ds_write_b32 v78, v118 offset:64
	ds_write_b32 v79, v119 offset:64
	ds_write_b32 v76, v120 offset:128
	ds_write_b32 v77, v121 offset:128
	ds_write_b32 v78, v122 offset:128
	ds_write_b32 v79, v123 offset:128
	ds_write_b32 v76, v124 offset:192
	ds_write_b32 v77, v125 offset:192
	ds_write_b32 v78, v126 offset:192
	ds_write_b32 v79, v127 offset:192
	s_branch .Lmy_ck_drE_a
.Lmy_ck_drB_a:
	s_waitcnt lgkmcnt(0)
	ds_read_b32 v88, v72 offset:16384
	ds_read_b32 v89, v72 offset:16640
	ds_read_b32 v90, v72 offset:16896
	ds_read_b32 v91, v72 offset:17152
	ds_read_b32 v92, v72 offset:17408
	ds_read_b32 v93, v72 offset:17664
	ds_read_b32 v94, v72 offset:17920
	ds_read_b32 v95, v72 offset:18176
	ds_read_b32 v96, v72 offset:24576
	ds_read_b32 v97, v72 offset:24832
	ds_read_b32 v98, v72 offset:25088
	ds_read_b32 v99, v72 offset:25344
	ds_read_b32 v100, v72 offset:25600
	ds_read_b32 v101, v72 offset:25856
	ds_read_b32 v102, v72 offset:26112
	ds_read_b32 v103, v72 offset:26368
	v_and_b32_e32 v74, 15, v224
	v_lshrrev_b32_e32 v76, 4, v224
	v_lshlrev_b32_e32 v74, 4, v74
	v_lshl_add_u32 v74, v76, 10, v74
	s_add_i32 s101, s97, 0x1000
	v_add_u32_e32 v74, s101, v74
	s_add_i32 s101, s97, 0x2000
	v_lshl_add_u32 v75, v224, 2, s101
	v_mov_b32_e32 v104, v80
	v_mul_f32_e32 v105, v104, v81
	v_mul_f32_e32 v106, v105, v82
	v_mul_f32_e32 v107, v106, v83
	v_mul_f32_e32 v108, v107, v84
	v_mul_f32_e32 v109, v108, v85
	v_mul_f32_e32 v110, v109, v86
	v_mul_f32_e32 v111, v110, v87
	v_rcp_f32_e32 v112, v104
	v_rcp_f32_e32 v113, v105
	v_rcp_f32_e32 v114, v106
	v_rcp_f32_e32 v115, v107
	v_rcp_f32_e32 v116, v108
	v_rcp_f32_e32 v117, v109
	v_rcp_f32_e32 v118, v110
	v_rcp_f32_e32 v119, v111
	s_waitcnt lgkmcnt(0)
	v_mul_f32_e32 v120, v112, v96
	v_mul_f32_e32 v121, v113, v97
	v_mul_f32_e32 v122, v114, v98
	v_mul_f32_e32 v123, v115, v99
	v_mul_f32_e32 v124, v116, v100
	v_mul_f32_e32 v125, v117, v101
	v_mul_f32_e32 v126, v118, v102
	v_mul_f32_e32 v127, v119, v103
	v_mul_f32_e32 v112, v112, v88
	v_mul_f32_e32 v113, v113, v89
	v_mul_f32_e32 v114, v114, v90
	v_mul_f32_e32 v115, v115, v91
	v_mul_f32_e32 v116, v116, v92
	v_mul_f32_e32 v117, v117, v93
	v_mul_f32_e32 v118, v118, v94
	v_mul_f32_e32 v119, v119, v95
	ds_write_b128 v74, v[112:115]
	ds_write_b128 v74, v[116:119] offset:256
	ds_write_b128 v74, v[120:123] offset:512
	ds_write_b128 v74, v[124:127] offset:768
	ds_write_b32 v75, v111
.Lmy_ck_drE_a:
	s_waitcnt lgkmcnt(0)
	s_barrier
	s_cmpk_ge_u32 s62, 0x100
	s_cbranch_scc1 .Lmy_ck_mE_a
	s_bfe_u32 s96, s62, 0x20006
	s_mul_i32 s97, s96, 0x2700
	s_cmp_gt_u32 s96, 1
	s_cselect_b32 s101, 0x1300, 0
	s_add_i32 s97, s97, s101
	s_add_i32 s97, s97, 0x1c000
	s_mov_b32 s96, s97
	v_and_b32_e32 v72, 3, v233
	v_lshrrev_b32_e32 v73, 2, v233
	v_lshlrev_b32_e32 v72, 2, v72
	v_lshl_add_u32 v72, v73, 8, v72
	v_lshl_add_u32 v72, v234, 6, v72
	s_add_i32 s97, s96, 0x1000
	v_add_u32_e32 v78, s97, v72
	v_xor_b32_e32 v79, v224, v234
	v_lshl_add_u32 v79, v79, 4, s96
	ds_read_b128 v[96:99], v79
	ds_read_b128 v[100:103], v79 offset:1024
	ds_read_b128 v[104:107], v79 offset:2048
	ds_read_b128 v[108:111], v79 offset:3072
	ds_read_b32 v80, v78
	ds_read_b32 v81, v78 offset:16
	ds_read_b32 v82, v78 offset:32
	ds_read_b32 v83, v78 offset:48
	ds_read_b32 v84, v78 offset:1024
	ds_read_b32 v85, v78 offset:1040
	ds_read_b32 v86, v78 offset:1056
	ds_read_b32 v87, v78 offset:1072
	ds_read_b32 v88, v78 offset:2048
	ds_read_b32 v89, v78 offset:2064
	ds_read_b32 v90, v78 offset:2080
	ds_read_b32 v91, v78 offset:2096
	ds_read_b32 v92, v78 offset:3072
	ds_read_b32 v93, v78 offset:3088
	ds_read_b32 v94, v78 offset:3104
	ds_read_b32 v95, v78 offset:3120
	v_lshl_add_u32 v74, v224, 2, s96
	ds_write_b32 v74, v235 offset:9728
	v_add_u32_e32 v75, -1, v233
	v_mov_b32_e32 v76, -1
	v_cndmask_b32_e64 v75, v76, v75, s[98:99]
	v_cmp_lt_u32_e64 s[100:101], 7, v233
	v_add_u32_e32 v76, -8, v233
	v_and_b32_e32 v77, 1, v234
	v_cndmask_b32_e64 v75, v75, v76, s[100:101]
	v_lshlrev_b32_e32 v77, 2, v77
	v_sub_u32_e32 v76, v75, v77
	v_lshlrev_b32_e32 v77, 2, v234
	v_sub_u32_e32 v77, v233, v77
	v_add_u32_e32 v77, -1, v77
	s_waitcnt lgkmcnt(10)
	v_mfma_f32_16x16x4_f32 v[244:247], v80, v96, 0
	v_mfma_f32_16x16x4_f32 v[240:243], v81, v97, 0
	v_mfma_f32_16x16x4_f32 v[244:247], v82, v98, v[244:247]
	v_mfma_f32_16x16x4_f32 v[240:243], v83, v99, v[240:243]
	v_mfma_f32_16x16x4_f32 v[244:247], v84, v100, v[244:247]
	v_mfma_f32_16x16x4_f32 v[240:243], v85, v101, v[240:243]
	v_mfma_f32_16x16x4_f32 v[244:247], v86, v102, v[244:247]
	s_waitcnt lgkmcnt(2)
	v_mfma_f32_16x16x4_f32 v[240:243], v87, v103, v[240:243]
	v_mfma_f32_16x16x4_f32 v[244:247], v88, v104, v[244:247]
	v_mfma_f32_16x16x4_f32 v[240:243], v89, v105, v[240:243]
	v_mfma_f32_16x16x4_f32 v[244:247], v90, v106, v[244:247]
	v_mfma_f32_16x16x4_f32 v[240:243], v91, v107, v[240:243]
	v_mfma_f32_16x16x4_f32 v[244:247], v92, v108, v[244:247]
	v_mfma_f32_16x16x4_f32 v[240:243], v93, v109, v[240:243]
	v_mfma_f32_16x16x4_f32 v[244:247], v94, v110, v[244:247]
	s_waitcnt lgkmcnt(1)
	v_mfma_f32_16x16x4_f32 v[240:243], v95, v111, v[240:243]
	s_nop 9
	v_add_f32_e32 v244, v244, v240
	v_add_f32_e32 v245, v245, v241
	v_add_f32_e32 v246, v246, v242
	v_add_f32_e32 v247, v247, v243
	v_cmp_le_i32_e64 s[96:97], 0, v76
	v_cmp_le_i32_e64 s[100:101], 1, v76
	s_nop 0
	v_cndmask_b32_e64 v128, 0, v244, s[96:97]
	v_cndmask_b32_e64 v129, 0, v245, s[100:101]
	v_cmp_le_i32_e64 s[96:97], 2, v76
	v_cmp_le_i32_e64 s[100:101], 3, v76
	s_nop 0
	v_cndmask_b32_e64 v130, 0, v246, s[96:97]
	v_cndmask_b32_e64 v131, 0, v247, s[100:101]
	s_bfe_u32 s96, s62, 0x20006
	s_mul_i32 s97, s96, 0x2700
	s_cmp_gt_u32 s96, 1
	s_cselect_b32 s101, 0x1300, 0
	s_add_i32 s97, s97, s101
	s_add_i32 s97, s97, 0x1c000
	v_xor_b32_e32 v74, v224, v234
	v_lshl_add_u32 v74, v74, 4, s97
	ds_write_b128 v74, v[128:131] offset:8448
	v_lshlrev_b32_e32 v75, 7, v234
	v_lshl_add_u32 v75, v233, 2, v75
	v_add_u32_e32 v75, s97, v75
	v_cmp_le_i32_e64 s[96:97], 0, v77
	v_cmp_le_i32_e64 s[100:101], 1, v77
	s_nop 0
	v_cndmask_b32_e64 v132, 0, v244, s[96:97]
	v_cndmask_b32_e64 v133, 0, v245, s[100:101]
	v_cmp_le_i32_e64 s[96:97], 2, v77
	v_cmp_le_i32_e64 s[100:101], 3, v77
	s_nop 0
	v_cndmask_b32_e64 v134, 0, v246, s[96:97]
	v_cndmask_b32_e64 v135, 0, v247, s[100:101]
	s_mov_b64 exec, 0x00ff00ff
	ds_write_b32 v75, v132 offset:9472
	ds_write_b32 v75, v133 offset:9504
	ds_write_b32 v75, v134 offset:9536
	ds_write_b32 v75, v135 offset:9568
	s_mov_b64 exec, -1

.Lmy_ck_nz:
	s_mov_b32 s100, 0xe000
	s_cmp_eq_u32 s23, 0
	s_cselect_b32 s100, 0x1c000, s100
	v_lshl_add_u32 v236, v224, 4, s100
	v_xor_b32_e32 v225, v224, v234
	v_lshl_add_u32 v225, v225, 4, s100
	s_add_i32 s101, s100, 0x2000
	v_lshl_add_u32 v226, v234, 4, s101
	s_add_i32 s101, s100, 0x2600
	v_mov_b32_e32 v72, s101
	v_cmp_eq_u32_e64 s[96:97], 0, v234
	s_add_i32 s101, s100, 0x2500
	v_mov_b32_e32 v73, s101
	s_add_i32 s101, s100, 0x2510
	v_mov_b32_e32 v74, s101
	v_cndmask_b32_e64 v227, v72, v73, s[96:97]
	v_cmp_eq_u32_e64 s[96:97], 1, v234
	s_add_i32 s101, s100, 0x2590
	v_mov_b32_e32 v75, s101
	v_and_b32_e32 v76, 1, v234
	v_cndmask_b32_e64 v228, v72, v74, s[96:97]
	v_cndmask_b32_e64 v229, v72, v75, s[96:97]
	v_lshlrev_b32_e32 v76, 10, v76
	v_lshl_add_u32 v76, v233, 2, v76
	v_add_u32_e32 v76, s62, v76
	s_lshl_b32 s96, s23, 13
	s_add_i32 s96, s96, 0xa000
	v_add_u32_e32 v230, s96, v76
	v_lshlrev_b32_e32 v77, 9, v234
	v_lshl_add_u32 v77, v233, 2, v77
	v_add_u32_e32 v77, s62, v77
	v_add_u32_e32 v239, s96, v77
	v_lshrrev_b32_e32 v77, 1, v234
	v_and_b32_e32 v78, 1, v234
	v_add_u32_e32 v79, 2, v77
	v_lshl_add_u32 v237, v79, 4, v233
	v_xor_b32_e32 v237, v237, v79
	v_lshlrev_b32_e32 v237, 4, v237
	v_lshl_add_u32 v237, v78, 3, v237
	s_add_i32 s101, s100, 0x2100
	v_add_u32_e32 v237, s101, v237
	v_lshl_add_u32 v238, v78, 4, v233
	v_xor_b32_e32 v238, v238, v78
	v_lshlrev_b32_e32 v238, 4, v238
	v_lshl_add_u32 v238, v77, 3, v238
	v_add_u32_e32 v238, s101, v238
	s_lshl_b32 s96, s23, 13
	s_add_i32 s96, s96, 0x18000
	v_add_u32_e32 v231, s96, v76
	v_add_u32_e32 v232, 48, v224
	v_and_b32_e32 v232, 63, v232
	v_lshlrev_b32_e32 v232, 2, v232
	s_mov_b32 s100, 0x6100
	s_cmp_eq_u32 s23, 0
	s_cselect_b32 s100, s100, 0x4e00
	v_add_u32_e32 v26, s100, v225
	v_add_u32_e32 v27, s100, v236
	v_add_u32_e32 v28, s100, v226
	v_add_u32_e32 v29, s100, v227
	v_add_u32_e32 v30, s100, v228
	v_add_u32_e32 v31, s100, v229
	v_add_u32_e32 v32, s100, v237
	v_add_u32_e32 v33, s100, v238
	ds_read_b64 v[80:81], v237
	ds_read_b64 v[82:83], v238
	ds_read_b32 v84, v230
	ds_read_b32 v85, v230 offset:256
	ds_read_b32 v86, v230 offset:512
	ds_read_b32 v87, v230 offset:768
	ds_read_b32 v36, v239
	ds_read_b32 v37, v239 offset:256
	ds_read_b128 v[88:91], v225
	ds_read_b128 v[92:95], v225 offset:1024
	ds_read_b128 v[96:99], v225 offset:2048
	ds_read_b128 v[100:103], v225 offset:3072
	ds_read_b32 v104, v227 offset:4
	ds_read_b32 v105, v227 offset:76
	ds_read_b64 v[106:107], v227 offset:8
	ds_read_b64 v[108:109], v227 offset:40
	ds_read_b32 v126, v229 offset:4
	ds_read_b32 v127, v229 offset:76
	ds_read_b64 v[128:129], v229 offset:8
	ds_read_b64 v[130:131], v229 offset:40
	ds_read_b64 v[110:111], v228
	ds_read_b64 v[112:113], v228 offset:32
	ds_read_b64 v[114:115], v228 offset:64
	ds_read_b64 v[116:117], v228 offset:96
	ds_read_b64 v[118:119], v228 offset:8
	ds_read_b64 v[120:121], v228 offset:40
	ds_read_b64 v[122:123], v228 offset:72
	ds_read_b64 v[124:125], v228 offset:104
	s_waitcnt lgkmcnt(15)
	v_mfma_f32_16x16x4_f32 v[240:243], v80, v36, 0
	v_mfma_f32_16x16x4_f32 v[240:243], v81, v37, v[240:243]
	v_mfma_f32_16x16x4_f32 v[240:243], v88, v208, v[240:243]
	ds_read_b128 v[184:187], v236 offset:4096
	ds_read_b128 v[188:191], v236 offset:5120
	v_mfma_f32_16x16x4_f32 v[244:247], v89, v209, 0
	ds_read_b128 v[192:195], v236 offset:6144
	ds_read_b128 v[196:199], v236 offset:7168
	v_mfma_f32_16x16x4_f32 v[240:243], v90, v210, v[240:243]
	ds_read_b64 v[132:133], v237 offset:9984
	ds_read_b64 v[134:135], v238 offset:9984
	v_mfma_f32_16x16x4_f32 v[244:247], v91, v211, v[244:247]
	ds_read_b32 v136, v230 offset:2048
	ds_read_b32 v137, v230 offset:2304
	v_mfma_f32_16x16x4_f32 v[240:243], v92, v212, v[240:243]
	ds_read_b32 v138, v230 offset:2560
	ds_read_b32 v139, v230 offset:2816
	v_mfma_f32_16x16x4_f32 v[244:247], v93, v213, v[244:247]
	ds_read_b32 v38, v239 offset:2048
	ds_read_b32 v39, v239 offset:2304
	v_mfma_f32_16x16x4_f32 v[240:243], v94, v214, v[240:243]
	ds_read_b128 v[140:143], v225 offset:9984
	ds_read_b128 v[144:147], v225 offset:11008
	v_mfma_f32_16x16x4_f32 v[244:247], v95, v215, v[244:247]
	ds_read_b128 v[148:151], v225 offset:12032
	ds_read_b128 v[152:155], v225 offset:13056
	v_mfma_f32_16x16x4_f32 v[240:243], v96, v216, v[240:243]
	ds_read_b32 v156, v227 offset:9988
	ds_read_b32 v157, v227 offset:10060
	v_mfma_f32_16x16x4_f32 v[244:247], v97, v217, v[244:247]
	ds_read_b64 v[158:159], v227 offset:9992
	ds_read_b64 v[160:161], v227 offset:10024
	v_mfma_f32_16x16x4_f32 v[240:243], v98, v218, v[240:243]
	ds_read_b32 v178, v229 offset:9988
	ds_read_b32 v179, v229 offset:10060
	v_mfma_f32_16x16x4_f32 v[244:247], v99, v219, v[244:247]
	ds_read_b64 v[180:181], v229 offset:9992
	ds_read_b64 v[182:183], v229 offset:10024
	v_mfma_f32_16x16x4_f32 v[240:243], v100, v220, v[240:243]
	ds_read_b64 v[162:163], v228 offset:9984
	ds_read_b64 v[164:165], v228 offset:10016
	v_mfma_f32_16x16x4_f32 v[244:247], v101, v221, v[244:247]
	ds_read_b64 v[166:167], v228 offset:10048
	ds_read_b64 v[168:169], v228 offset:10080
	v_mfma_f32_16x16x4_f32 v[240:243], v102, v222, v[240:243]
	ds_read_b64 v[170:171], v228 offset:9992
	ds_read_b64 v[172:173], v228 offset:10024
	v_mfma_f32_16x16x4_f32 v[244:247], v103, v223, v[244:247]
	ds_read_b64 v[174:175], v228 offset:10056
	ds_read_b64 v[176:177], v228 offset:10088
	s_nop 7
	v_pk_add_f32 v[240:241], v[240:241], v[244:245]
	v_pk_add_f32 v[242:243], v[242:243], v[246:247]
	v_fmac_f32_e32 v241, v104, v240
	s_waitcnt lgkmcnt(13)
	v_pk_fma_f32 v[242:243], v[106:107], v[240:241], v[242:243] op_sel:[0,0,0] op_sel_hi:[1,0,1]
	v_pk_fma_f32 v[242:243], v[108:109], v[240:241], v[242:243] op_sel:[0,1,0] op_sel_hi:[1,1,1]
	v_fmac_f32_e32 v243, v105, v242
	ds_bpermute_b32 v204, v232, v240
	ds_bpermute_b32 v205, v232, v241
	ds_bpermute_b32 v206, v232, v242
	ds_bpermute_b32 v207, v232, v243
	ds_read_b128 v[88:91], v226
	ds_read_b128 v[92:95], v226 offset:64
	ds_read_b128 v[96:99], v226 offset:128
	ds_read_b128 v[100:103], v226 offset:192
	v_mfma_f32_16x16x4_f32 v[72:75], v132, v38, 0
	v_mfma_f32_16x16x4_f32 v[72:75], v133, v39, v[72:75]
	s_waitcnt lgkmcnt(6)
	v_pk_fma_f32 v[240:241], v[110:111], v[204:205], v[240:241] op_sel:[0,0,0] op_sel_hi:[1,0,1]
	v_pk_fma_f32 v[240:241], v[112:113], v[204:205], v[240:241] op_sel:[0,1,0] op_sel_hi:[1,1,1]
	s_waitcnt lgkmcnt(4)
	v_pk_fma_f32 v[240:241], v[114:115], v[206:207], v[240:241] op_sel:[0,0,0] op_sel_hi:[1,0,1]
	v_pk_fma_f32 v[240:241], v[116:117], v[206:207], v[240:241] op_sel:[0,1,0] op_sel_hi:[1,1,1]
	v_pk_fma_f32 v[242:243], v[118:119], v[204:205], v[242:243] op_sel:[0,0,0] op_sel_hi:[1,0,1]
	v_pk_fma_f32 v[242:243], v[120:121], v[204:205], v[242:243] op_sel:[0,1,0] op_sel_hi:[1,1,1]
	v_pk_fma_f32 v[242:243], v[122:123], v[206:207], v[242:243] op_sel:[0,0,0] op_sel_hi:[1,0,1]
	v_pk_fma_f32 v[242:243], v[124:125], v[206:207], v[242:243] op_sel:[0,1,0] op_sel_hi:[1,1,1]
	v_fmac_f32_e32 v241, v126, v240
	v_pk_fma_f32 v[242:243], v[128:129], v[240:241], v[242:243] op_sel:[0,0,0] op_sel_hi:[1,0,1]
	v_pk_fma_f32 v[242:243], v[130:131], v[240:241], v[242:243] op_sel:[0,1,0] op_sel_hi:[1,1,1]
	v_fmac_f32_e32 v243, v127, v242
	v_cndmask_b32_e64 v200, v240, v84, s[98:99]
	v_cndmask_b32_e64 v201, v241, v85, s[98:99]
	v_cndmask_b32_e64 v202, v242, v86, s[98:99]
	v_cndmask_b32_e64 v203, v243, v87, s[98:99]
	v_mov_b32_e32 v252, v240
	v_mov_b32_e32 v253, v241
	v_mov_b32_e32 v254, v242
	v_mov_b32_e32 v255, v243
	v_mfma_f32_16x16x4_f32 v[208:211], v184, v200, v[208:211]
	v_mfma_f32_16x16x4_f32 v[212:215], v188, v200, v[212:215]
	v_mfma_f32_16x16x4_f32 v[216:219], v192, v200, v[216:219]
	v_mfma_f32_16x16x4_f32 v[220:223], v196, v200, v[220:223]
	v_permlane32_swap_b32_e32 v252, v254
	v_permlane32_swap_b32_e32 v253, v255
	v_mfma_f32_16x16x4_f32 v[208:211], v185, v201, v[208:211]
	v_mfma_f32_16x16x4_f32 v[212:215], v189, v201, v[212:215]
	v_mfma_f32_16x16x4_f32 v[216:219], v193, v201, v[216:219]
	v_mfma_f32_16x16x4_f32 v[220:223], v197, v201, v[220:223]
	v_mfma_f32_16x16x4_f32 v[208:211], v186, v202, v[208:211]
	v_mfma_f32_16x16x4_f32 v[212:215], v190, v202, v[212:215]
	v_mfma_f32_16x16x4_f32 v[216:219], v194, v202, v[216:219]
	v_mfma_f32_16x16x4_f32 v[220:223], v198, v202, v[220:223]
	v_mfma_f32_16x16x4_f32 v[208:211], v187, v203, v[208:211]
	v_mfma_f32_16x16x4_f32 v[212:215], v191, v203, v[212:215]
	v_mfma_f32_16x16x4_f32 v[216:219], v195, v203, v[216:219]
	v_mfma_f32_16x16x4_f32 v[220:223], v199, v203, v[220:223]
	v_mfma_f32_16x16x4_f32 v[248:251], v82, v252, v[240:243]
	v_mfma_f32_16x16x4_f32 v[248:251], v83, v253, v[248:251]
	s_waitcnt lgkmcnt(0)
	s_nop 4
	v_pk_mul_f32 v[208:209], v[208:209], v[88:89]
	v_pk_mul_f32 v[210:211], v[210:211], v[90:91]
	s_nop 0
	v_mfma_f32_16x16x4_f32 v[72:75], v140, v208, v[72:75]
	v_pk_mul_f32 v[212:213], v[212:213], v[92:93]
	v_mfma_f32_16x16x4_f32 v[244:247], v141, v209, 0
	v_pk_mul_f32 v[214:215], v[214:215], v[94:95]
	v_mfma_f32_16x16x4_f32 v[72:75], v142, v210, v[72:75]
	v_pk_mul_f32 v[216:217], v[216:217], v[96:97]
	v_mfma_f32_16x16x4_f32 v[244:247], v143, v211, v[244:247]
	v_pk_mul_f32 v[218:219], v[218:219], v[98:99]
	v_mfma_f32_16x16x4_f32 v[72:75], v144, v212, v[72:75]
	v_pk_mul_f32 v[220:221], v[220:221], v[100:101]
	v_mfma_f32_16x16x4_f32 v[244:247], v145, v213, v[244:247]
	v_pk_mul_f32 v[222:223], v[222:223], v[102:103]
	v_mfma_f32_16x16x4_f32 v[72:75], v146, v214, v[72:75]
	s_mov_b64 exec, s[98:99]
	ds_write_b32 v231, v248
	ds_write_b32 v231, v249 offset:256
	ds_write_b32 v231, v250 offset:512
	ds_write_b32 v231, v251 offset:768
	s_mov_b64 exec, -1
	ds_read_b128 v[184:187], v236 offset:14080
	ds_read_b128 v[188:191], v236 offset:15104
	v_mfma_f32_16x16x4_f32 v[244:247], v147, v215, v[244:247]
	ds_read_b128 v[192:195], v236 offset:16128
	ds_read_b128 v[196:199], v236 offset:17152
	v_mfma_f32_16x16x4_f32 v[72:75], v148, v216, v[72:75]
	ds_read_b64 v[80:81], v32
	ds_read_b64 v[82:83], v33
	ds_read_b32 v84, v230 offset:4096
	ds_read_b32 v85, v230 offset:4352
	v_mfma_f32_16x16x4_f32 v[244:247], v149, v217, v[244:247]
	ds_read_b32 v86, v230 offset:4608
	ds_read_b32 v87, v230 offset:4864
	ds_read_b32 v36, v239 offset:4096
	ds_read_b32 v37, v239 offset:4352
	v_mfma_f32_16x16x4_f32 v[72:75], v150, v218, v[72:75]
	ds_read_b128 v[88:91], v26
	ds_read_b128 v[92:95], v26 offset:1024
	ds_read_b128 v[96:99], v26 offset:2048
	ds_read_b128 v[100:103], v26 offset:3072
	v_mfma_f32_16x16x4_f32 v[244:247], v151, v219, v[244:247]
	ds_read_b32 v104, v29 offset:4
	ds_read_b32 v105, v29 offset:76
	ds_read_b64 v[106:107], v29 offset:8
	ds_read_b64 v[108:109], v29 offset:40
	v_mfma_f32_16x16x4_f32 v[72:75], v152, v220, v[72:75]
	ds_read_b32 v126, v31 offset:4
	ds_read_b32 v127, v31 offset:76
	ds_read_b64 v[128:129], v31 offset:8
	ds_read_b64 v[130:131], v31 offset:40
	v_mfma_f32_16x16x4_f32 v[244:247], v153, v221, v[244:247]
	ds_read_b64 v[110:111], v30
	ds_read_b64 v[112:113], v30 offset:32
	ds_read_b64 v[114:115], v30 offset:64
	ds_read_b64 v[116:117], v30 offset:96
	v_mfma_f32_16x16x4_f32 v[72:75], v154, v222, v[72:75]
	ds_read_b64 v[118:119], v30 offset:8
	ds_read_b64 v[120:121], v30 offset:40
	ds_read_b64 v[122:123], v30 offset:72
	ds_read_b64 v[124:125], v30 offset:104
	v_mfma_f32_16x16x4_f32 v[244:247], v155, v223, v[244:247]
	s_nop 9
	v_pk_add_f32 v[72:73], v[72:73], v[244:245]
	v_pk_add_f32 v[74:75], v[74:75], v[246:247]
	v_fmac_f32_e32 v73, v156, v72
	v_pk_fma_f32 v[74:75], v[158:159], v[72:73], v[74:75] op_sel:[0,0,0] op_sel_hi:[1,0,1]
	v_pk_fma_f32 v[74:75], v[160:161], v[72:73], v[74:75] op_sel:[0,1,0] op_sel_hi:[1,1,1]
	v_fmac_f32_e32 v75, v157, v74
	ds_bpermute_b32 v204, v232, v72
	ds_bpermute_b32 v205, v232, v73
	ds_bpermute_b32 v206, v232, v74
	ds_bpermute_b32 v207, v232, v75
	ds_read_b128 v[140:143], v226 offset:9984
	ds_read_b128 v[144:147], v226 offset:10048
	ds_read_b128 v[148:151], v226 offset:10112
	ds_read_b128 v[152:155], v226 offset:10176
	s_waitcnt lgkmcnt(14)
	v_mfma_f32_16x16x4_f32 v[240:243], v80, v36, 0
	v_mfma_f32_16x16x4_f32 v[240:243], v81, v37, v[240:243]
	s_waitcnt lgkmcnt(6)
	v_pk_fma_f32 v[72:73], v[162:163], v[204:205], v[72:73] op_sel:[0,0,0] op_sel_hi:[1,0,1]
	v_pk_fma_f32 v[72:73], v[164:165], v[204:205], v[72:73] op_sel:[0,1,0] op_sel_hi:[1,1,1]
	s_waitcnt lgkmcnt(4)
	v_pk_fma_f32 v[72:73], v[166:167], v[206:207], v[72:73] op_sel:[0,0,0] op_sel_hi:[1,0,1]
	v_pk_fma_f32 v[72:73], v[168:169], v[206:207], v[72:73] op_sel:[0,1,0] op_sel_hi:[1,1,1]
	v_pk_fma_f32 v[74:75], v[170:171], v[204:205], v[74:75] op_sel:[0,0,0] op_sel_hi:[1,0,1]
	v_pk_fma_f32 v[74:75], v[172:173], v[204:205], v[74:75] op_sel:[0,1,0] op_sel_hi:[1,1,1]
	v_pk_fma_f32 v[74:75], v[174:175], v[206:207], v[74:75] op_sel:[0,0,0] op_sel_hi:[1,0,1]
	v_pk_fma_f32 v[74:75], v[176:177], v[206:207], v[74:75] op_sel:[0,1,0] op_sel_hi:[1,1,1]
	v_fmac_f32_e32 v73, v178, v72
	v_pk_fma_f32 v[74:75], v[180:181], v[72:73], v[74:75] op_sel:[0,0,0] op_sel_hi:[1,0,1]
	v_pk_fma_f32 v[74:75], v[182:183], v[72:73], v[74:75] op_sel:[0,1,0] op_sel_hi:[1,1,1]
	v_fmac_f32_e32 v75, v179, v74
	v_cndmask_b32_e64 v200, v72, v136, s[98:99]
	v_cndmask_b32_e64 v201, v73, v137, s[98:99]
	v_cndmask_b32_e64 v202, v74, v138, s[98:99]
	v_cndmask_b32_e64 v203, v75, v139, s[98:99]
	v_mov_b32_e32 v252, v72
	v_mov_b32_e32 v253, v73
	v_mov_b32_e32 v254, v74
	v_mov_b32_e32 v255, v75
	v_mfma_f32_16x16x4_f32 v[208:211], v184, v200, v[208:211]
	v_mfma_f32_16x16x4_f32 v[212:215], v188, v200, v[212:215]
	v_mfma_f32_16x16x4_f32 v[216:219], v192, v200, v[216:219]
	v_mfma_f32_16x16x4_f32 v[220:223], v196, v200, v[220:223]
	v_permlane32_swap_b32_e32 v252, v254
	v_permlane32_swap_b32_e32 v253, v255
	v_mfma_f32_16x16x4_f32 v[208:211], v185, v201, v[208:211]
	v_mfma_f32_16x16x4_f32 v[212:215], v189, v201, v[212:215]
	v_mfma_f32_16x16x4_f32 v[216:219], v193, v201, v[216:219]
	v_mfma_f32_16x16x4_f32 v[220:223], v197, v201, v[220:223]
	v_mfma_f32_16x16x4_f32 v[208:211], v186, v202, v[208:211]
	v_mfma_f32_16x16x4_f32 v[212:215], v190, v202, v[212:215]
	v_mfma_f32_16x16x4_f32 v[216:219], v194, v202, v[216:219]
	v_mfma_f32_16x16x4_f32 v[220:223], v198, v202, v[220:223]
	v_mfma_f32_16x16x4_f32 v[208:211], v187, v203, v[208:211]
	v_mfma_f32_16x16x4_f32 v[212:215], v191, v203, v[212:215]
	v_mfma_f32_16x16x4_f32 v[216:219], v195, v203, v[216:219]
	v_mfma_f32_16x16x4_f32 v[220:223], v199, v203, v[220:223]
	v_mfma_f32_16x16x4_f32 v[248:251], v134, v252, v[72:75]
	v_mfma_f32_16x16x4_f32 v[248:251], v135, v253, v[248:251]
	s_waitcnt lgkmcnt(0)
	s_nop 4
	v_pk_mul_f32 v[208:209], v[208:209], v[140:141]
	v_pk_mul_f32 v[210:211], v[210:211], v[142:143]
	s_nop 0
	v_mfma_f32_16x16x4_f32 v[240:243], v88, v208, v[240:243]
	v_pk_mul_f32 v[212:213], v[212:213], v[144:145]
	v_mfma_f32_16x16x4_f32 v[244:247], v89, v209, 0
	v_pk_mul_f32 v[214:215], v[214:215], v[146:147]
	v_mfma_f32_16x16x4_f32 v[240:243], v90, v210, v[240:243]
	v_pk_mul_f32 v[216:217], v[216:217], v[148:149]
	v_mfma_f32_16x16x4_f32 v[244:247], v91, v211, v[244:247]
	v_pk_mul_f32 v[218:219], v[218:219], v[150:151]
	v_mfma_f32_16x16x4_f32 v[240:243], v92, v212, v[240:243]
	v_pk_mul_f32 v[220:221], v[220:221], v[152:153]
	v_mfma_f32_16x16x4_f32 v[244:247], v93, v213, v[244:247]
	v_pk_mul_f32 v[222:223], v[222:223], v[154:155]
	v_mfma_f32_16x16x4_f32 v[240:243], v94, v214, v[240:243]
	s_mov_b64 exec, s[98:99]
	ds_write_b32 v231, v248 offset:2048
	ds_write_b32 v231, v249 offset:2304
	ds_write_b32 v231, v250 offset:2560
	ds_write_b32 v231, v251 offset:2816
	s_mov_b64 exec, -1
	ds_read_b128 v[184:187], v27 offset:4096
	ds_read_b128 v[188:191], v27 offset:5120
	v_mfma_f32_16x16x4_f32 v[244:247], v95, v215, v[244:247]
	ds_read_b128 v[192:195], v27 offset:6144
	ds_read_b128 v[196:199], v27 offset:7168
	v_mfma_f32_16x16x4_f32 v[240:243], v96, v216, v[240:243]
	ds_read_b64 v[132:133], v32 offset:9984
	ds_read_b64 v[134:135], v33 offset:9984
	ds_read_b32 v136, v230 offset:6144
	ds_read_b32 v137, v230 offset:6400
	v_mfma_f32_16x16x4_f32 v[244:247], v97, v217, v[244:247]
	ds_read_b32 v138, v230 offset:6656
	ds_read_b32 v139, v230 offset:6912
	ds_read_b32 v38, v239 offset:6144
	ds_read_b32 v39, v239 offset:6400
	v_mfma_f32_16x16x4_f32 v[240:243], v98, v218, v[240:243]
	ds_read_b128 v[140:143], v26 offset:9984
	ds_read_b128 v[144:147], v26 offset:11008
	ds_read_b128 v[148:151], v26 offset:12032
	ds_read_b128 v[152:155], v26 offset:13056
	v_mfma_f32_16x16x4_f32 v[244:247], v99, v219, v[244:247]
	ds_read_b32 v156, v29 offset:9988
	ds_read_b32 v157, v29 offset:10060
	ds_read_b64 v[158:159], v29 offset:9992
	ds_read_b64 v[160:161], v29 offset:10024
	v_mfma_f32_16x16x4_f32 v[240:243], v100, v220, v[240:243]
	ds_read_b32 v178, v31 offset:9988
	ds_read_b32 v179, v31 offset:10060
	ds_read_b64 v[180:181], v31 offset:9992
	ds_read_b64 v[182:183], v31 offset:10024
	v_mfma_f32_16x16x4_f32 v[244:247], v101, v221, v[244:247]
	ds_read_b64 v[162:163], v30 offset:9984
	ds_read_b64 v[164:165], v30 offset:10016
	ds_read_b64 v[166:167], v30 offset:10048
	ds_read_b64 v[168:169], v30 offset:10080
	v_mfma_f32_16x16x4_f32 v[240:243], v102, v222, v[240:243]
	ds_read_b64 v[170:171], v30 offset:9992
	ds_read_b64 v[172:173], v30 offset:10024
	ds_read_b64 v[174:175], v30 offset:10056
	ds_read_b64 v[176:177], v30 offset:10088
	v_mfma_f32_16x16x4_f32 v[244:247], v103, v223, v[244:247]
	s_nop 9
	v_pk_add_f32 v[240:241], v[240:241], v[244:245]
	v_pk_add_f32 v[242:243], v[242:243], v[246:247]
	v_fmac_f32_e32 v241, v104, v240
	v_pk_fma_f32 v[242:243], v[106:107], v[240:241], v[242:243] op_sel:[0,0,0] op_sel_hi:[1,0,1]
	v_pk_fma_f32 v[242:243], v[108:109], v[240:241], v[242:243] op_sel:[0,1,0] op_sel_hi:[1,1,1]
	v_fmac_f32_e32 v243, v105, v242
	ds_bpermute_b32 v204, v232, v240
	ds_bpermute_b32 v205, v232, v241
	ds_bpermute_b32 v206, v232, v242
	ds_bpermute_b32 v207, v232, v243
	ds_read_b128 v[88:91], v28
	ds_read_b128 v[92:95], v28 offset:64
	ds_read_b128 v[96:99], v28 offset:128
	ds_read_b128 v[100:103], v28 offset:192
	s_waitcnt lgkmcnt(14)
	v_mfma_f32_16x16x4_f32 v[72:75], v132, v38, 0
	v_mfma_f32_16x16x4_f32 v[72:75], v133, v39, v[72:75]
	s_waitcnt lgkmcnt(6)
	v_pk_fma_f32 v[240:241], v[110:111], v[204:205], v[240:241] op_sel:[0,0,0] op_sel_hi:[1,0,1]
	v_pk_fma_f32 v[240:241], v[112:113], v[204:205], v[240:241] op_sel:[0,1,0] op_sel_hi:[1,1,1]
	s_waitcnt lgkmcnt(4)
	v_pk_fma_f32 v[240:241], v[114:115], v[206:207], v[240:241] op_sel:[0,0,0] op_sel_hi:[1,0,1]
	v_pk_fma_f32 v[240:241], v[116:117], v[206:207], v[240:241] op_sel:[0,1,0] op_sel_hi:[1,1,1]
	v_pk_fma_f32 v[242:243], v[118:119], v[204:205], v[242:243] op_sel:[0,0,0] op_sel_hi:[1,0,1]
	v_pk_fma_f32 v[242:243], v[120:121], v[204:205], v[242:243] op_sel:[0,1,0] op_sel_hi:[1,1,1]
	v_pk_fma_f32 v[242:243], v[122:123], v[206:207], v[242:243] op_sel:[0,0,0] op_sel_hi:[1,0,1]
	v_pk_fma_f32 v[242:243], v[124:125], v[206:207], v[242:243] op_sel:[0,1,0] op_sel_hi:[1,1,1]
	v_fmac_f32_e32 v241, v126, v240
	v_pk_fma_f32 v[242:243], v[128:129], v[240:241], v[242:243] op_sel:[0,0,0] op_sel_hi:[1,0,1]
	v_pk_fma_f32 v[242:243], v[130:131], v[240:241], v[242:243] op_sel:[0,1,0] op_sel_hi:[1,1,1]
	v_fmac_f32_e32 v243, v127, v242
	v_cndmask_b32_e64 v200, v240, v84, s[98:99]
	v_cndmask_b32_e64 v201, v241, v85, s[98:99]
	v_cndmask_b32_e64 v202, v242, v86, s[98:99]
	v_cndmask_b32_e64 v203, v243, v87, s[98:99]
	v_mov_b32_e32 v252, v240
	v_mov_b32_e32 v253, v241
	v_mov_b32_e32 v254, v242
	v_mov_b32_e32 v255, v243
	v_mfma_f32_16x16x4_f32 v[208:211], v184, v200, v[208:211]
	v_mfma_f32_16x16x4_f32 v[212:215], v188, v200, v[212:215]
	v_mfma_f32_16x16x4_f32 v[216:219], v192, v200, v[216:219]
	v_mfma_f32_16x16x4_f32 v[220:223], v196, v200, v[220:223]
	v_permlane32_swap_b32_e32 v252, v254
	v_permlane32_swap_b32_e32 v253, v255
	v_mfma_f32_16x16x4_f32 v[208:211], v185, v201, v[208:211]
	v_mfma_f32_16x16x4_f32 v[212:215], v189, v201, v[212:215]
	v_mfma_f32_16x16x4_f32 v[216:219], v193, v201, v[216:219]
	v_mfma_f32_16x16x4_f32 v[220:223], v197, v201, v[220:223]
	v_mfma_f32_16x16x4_f32 v[208:211], v186, v202, v[208:211]
	v_mfma_f32_16x16x4_f32 v[212:215], v190, v202, v[212:215]
	v_mfma_f32_16x16x4_f32 v[216:219], v194, v202, v[216:219]
	v_mfma_f32_16x16x4_f32 v[220:223], v198, v202, v[220:223]
	v_mfma_f32_16x16x4_f32 v[208:211], v187, v203, v[208:211]
	v_mfma_f32_16x16x4_f32 v[212:215], v191, v203, v[212:215]
	v_mfma_f32_16x16x4_f32 v[216:219], v195, v203, v[216:219]
	v_mfma_f32_16x16x4_f32 v[220:223], v199, v203, v[220:223]
	v_mfma_f32_16x16x4_f32 v[248:251], v82, v252, v[240:243]
	v_mfma_f32_16x16x4_f32 v[248:251], v83, v253, v[248:251]
	s_waitcnt lgkmcnt(0)
	s_nop 4
	v_pk_mul_f32 v[208:209], v[208:209], v[88:89]
	v_pk_mul_f32 v[210:211], v[210:211], v[90:91]
	s_nop 0
	v_mfma_f32_16x16x4_f32 v[72:75], v140, v208, v[72:75]
	v_pk_mul_f32 v[212:213], v[212:213], v[92:93]
	v_mfma_f32_16x16x4_f32 v[244:247], v141, v209, 0
	v_pk_mul_f32 v[214:215], v[214:215], v[94:95]
	v_mfma_f32_16x16x4_f32 v[72:75], v142, v210, v[72:75]
	v_pk_mul_f32 v[216:217], v[216:217], v[96:97]
	v_mfma_f32_16x16x4_f32 v[244:247], v143, v211, v[244:247]
	v_pk_mul_f32 v[218:219], v[218:219], v[98:99]
	v_mfma_f32_16x16x4_f32 v[72:75], v144, v212, v[72:75]
	v_pk_mul_f32 v[220:221], v[220:221], v[100:101]
	v_mfma_f32_16x16x4_f32 v[244:247], v145, v213, v[244:247]
	v_pk_mul_f32 v[222:223], v[222:223], v[102:103]
	v_mfma_f32_16x16x4_f32 v[72:75], v146, v214, v[72:75]
	s_mov_b64 exec, s[98:99]
	ds_write_b32 v231, v248 offset:4096
	ds_write_b32 v231, v249 offset:4352
	ds_write_b32 v231, v250 offset:4608
	ds_write_b32 v231, v251 offset:4864
	s_mov_b64 exec, -1
	ds_read_b128 v[184:187], v27 offset:14080
	ds_read_b128 v[188:191], v27 offset:15104
	v_mfma_f32_16x16x4_f32 v[244:247], v147, v215, v[244:247]
	ds_read_b128 v[192:195], v27 offset:16128
	ds_read_b128 v[196:199], v27 offset:17152
	v_mfma_f32_16x16x4_f32 v[72:75], v148, v216, v[72:75]
	v_mfma_f32_16x16x4_f32 v[244:247], v149, v217, v[244:247]
	v_mfma_f32_16x16x4_f32 v[72:75], v150, v218, v[72:75]
	v_mfma_f32_16x16x4_f32 v[244:247], v151, v219, v[244:247]
	v_mfma_f32_16x16x4_f32 v[72:75], v152, v220, v[72:75]
	v_mfma_f32_16x16x4_f32 v[244:247], v153, v221, v[244:247]
	v_mfma_f32_16x16x4_f32 v[72:75], v154, v222, v[72:75]
	v_mfma_f32_16x16x4_f32 v[244:247], v155, v223, v[244:247]
	s_nop 9
	v_pk_add_f32 v[72:73], v[72:73], v[244:245]
	v_pk_add_f32 v[74:75], v[74:75], v[246:247]
	v_fmac_f32_e32 v73, v156, v72
	v_pk_fma_f32 v[74:75], v[158:159], v[72:73], v[74:75] op_sel:[0,0,0] op_sel_hi:[1,0,1]
	v_pk_fma_f32 v[74:75], v[160:161], v[72:73], v[74:75] op_sel:[0,1,0] op_sel_hi:[1,1,1]
	v_fmac_f32_e32 v75, v157, v74
	ds_bpermute_b32 v204, v232, v72
	ds_bpermute_b32 v205, v232, v73
	ds_bpermute_b32 v206, v232, v74
	ds_bpermute_b32 v207, v232, v75
	ds_read_b128 v[140:143], v28 offset:9984
	ds_read_b128 v[144:147], v28 offset:10048
	ds_read_b128 v[148:151], v28 offset:10112
	ds_read_b128 v[152:155], v28 offset:10176
	s_waitcnt lgkmcnt(6)
	v_pk_fma_f32 v[72:73], v[162:163], v[204:205], v[72:73] op_sel:[0,0,0] op_sel_hi:[1,0,1]
	v_pk_fma_f32 v[72:73], v[164:165], v[204:205], v[72:73] op_sel:[0,1,0] op_sel_hi:[1,1,1]
	s_waitcnt lgkmcnt(4)
	v_pk_fma_f32 v[72:73], v[166:167], v[206:207], v[72:73] op_sel:[0,0,0] op_sel_hi:[1,0,1]
	v_pk_fma_f32 v[72:73], v[168:169], v[206:207], v[72:73] op_sel:[0,1,0] op_sel_hi:[1,1,1]
	v_pk_fma_f32 v[74:75], v[170:171], v[204:205], v[74:75] op_sel:[0,0,0] op_sel_hi:[1,0,1]
	v_pk_fma_f32 v[74:75], v[172:173], v[204:205], v[74:75] op_sel:[0,1,0] op_sel_hi:[1,1,1]
	v_pk_fma_f32 v[74:75], v[174:175], v[206:207], v[74:75] op_sel:[0,0,0] op_sel_hi:[1,0,1]
	v_pk_fma_f32 v[74:75], v[176:177], v[206:207], v[74:75] op_sel:[0,1,0] op_sel_hi:[1,1,1]
	v_fmac_f32_e32 v73, v178, v72
	v_pk_fma_f32 v[74:75], v[180:181], v[72:73], v[74:75] op_sel:[0,0,0] op_sel_hi:[1,0,1]
	v_pk_fma_f32 v[74:75], v[182:183], v[72:73], v[74:75] op_sel:[0,1,0] op_sel_hi:[1,1,1]
	v_fmac_f32_e32 v75, v179, v74
	v_cndmask_b32_e64 v200, v72, v136, s[98:99]
	v_cndmask_b32_e64 v201, v73, v137, s[98:99]
	v_cndmask_b32_e64 v202, v74, v138, s[98:99]
	v_cndmask_b32_e64 v203, v75, v139, s[98:99]
	v_mov_b32_e32 v252, v72
	v_mov_b32_e32 v253, v73
	v_mov_b32_e32 v254, v74
	v_mov_b32_e32 v255, v75
	v_mfma_f32_16x16x4_f32 v[208:211], v184, v200, v[208:211]
	v_mfma_f32_16x16x4_f32 v[212:215], v188, v200, v[212:215]
	v_mfma_f32_16x16x4_f32 v[216:219], v192, v200, v[216:219]
	v_mfma_f32_16x16x4_f32 v[220:223], v196, v200, v[220:223]
	v_permlane32_swap_b32_e32 v252, v254
	v_permlane32_swap_b32_e32 v253, v255
	v_mfma_f32_16x16x4_f32 v[208:211], v185, v201, v[208:211]
	v_mfma_f32_16x16x4_f32 v[212:215], v189, v201, v[212:215]
	v_mfma_f32_16x16x4_f32 v[216:219], v193, v201, v[216:219]
	v_mfma_f32_16x16x4_f32 v[220:223], v197, v201, v[220:223]
	v_mfma_f32_16x16x4_f32 v[208:211], v186, v202, v[208:211]
	v_mfma_f32_16x16x4_f32 v[212:215], v190, v202, v[212:215]
	v_mfma_f32_16x16x4_f32 v[216:219], v194, v202, v[216:219]
	v_mfma_f32_16x16x4_f32 v[220:223], v198, v202, v[220:223]
	v_mfma_f32_16x16x4_f32 v[208:211], v187, v203, v[208:211]
	v_mfma_f32_16x16x4_f32 v[212:215], v191, v203, v[212:215]
	v_mfma_f32_16x16x4_f32 v[216:219], v195, v203, v[216:219]
	v_mfma_f32_16x16x4_f32 v[220:223], v199, v203, v[220:223]
	v_mfma_f32_16x16x4_f32 v[248:251], v134, v252, v[72:75]
	v_mfma_f32_16x16x4_f32 v[248:251], v135, v253, v[248:251]
	s_waitcnt lgkmcnt(0)
	s_nop 4
	v_pk_mul_f32 v[208:209], v[208:209], v[140:141]
	v_pk_mul_f32 v[210:211], v[210:211], v[142:143]
	v_pk_mul_f32 v[212:213], v[212:213], v[144:145]
	v_pk_mul_f32 v[214:215], v[214:215], v[146:147]
	v_pk_mul_f32 v[216:217], v[216:217], v[148:149]
	v_pk_mul_f32 v[218:219], v[218:219], v[150:151]
	v_pk_mul_f32 v[220:221], v[220:221], v[152:153]
	v_pk_mul_f32 v[222:223], v[222:223], v[154:155]
	s_mov_b64 exec, s[98:99]
	ds_write_b32 v231, v248 offset:6144
	ds_write_b32 v231, v249 offset:6400
	ds_write_b32 v231, v250 offset:6656
	ds_write_b32 v231, v251 offset:6912
	s_mov_b64 exec, -1
	s_branch .LBB0_655

.Lmy_f_nol34:
	s_waitcnt lgkmcnt(0)
	s_bfe_u32 s96, s62, 0x20006
	s_lshl_b32 s100, s96, 11
	v_lshl_add_u32 v72, v224, 2, s100
	s_and_b32 s97, s96, 1
	s_mul_i32 s97, s97, 0x2700
	s_mov_b32 s101, 0x1c000
	s_mov_b32 s100, 0x6100
	s_bitcmp0_b32 s65, 0
	s_cselect_b32 s101, 0xe000, s101
	s_cselect_b32 s100, 0x4e00, s100
	s_cmp_gt_u32 s96, 1
	s_cselect_b32 s100, s100, 0
	s_add_i32 s97, s97, s101
	s_add_i32 s97, s97, s100
	ds_read_b32 v80, v72
	ds_read_b32 v81, v72 offset:256
	ds_read_b32 v82, v72 offset:512
	ds_read_b32 v83, v72 offset:768
	ds_read_b32 v84, v72 offset:1024
	ds_read_b32 v85, v72 offset:1280
	ds_read_b32 v86, v72 offset:1536
	ds_read_b32 v87, v72 offset:1792
	ds_read_b32 v88, v72 offset:8192
	ds_read_b32 v89, v72 offset:8448
	ds_read_b32 v90, v72 offset:8704
	ds_read_b32 v91, v72 offset:8960
	ds_read_b32 v92, v72 offset:9216
	ds_read_b32 v93, v72 offset:9472
	ds_read_b32 v94, v72 offset:9728
	ds_read_b32 v95, v72 offset:9984
	ds_read_b32 v96, v72 offset:32768
	ds_read_b32 v97, v72 offset:33024
	ds_read_b32 v98, v72 offset:33280
	ds_read_b32 v99, v72 offset:33536
	ds_read_b32 v100, v72 offset:33792
	ds_read_b32 v101, v72 offset:34048
	ds_read_b32 v102, v72 offset:34304
	ds_read_b32 v103, v72 offset:34560
	v_and_b32_e32 v74, 3, v224
	v_bfe_u32 v75, v224, 2, 2
	v_lshrrev_b32_e32 v76, 4, v224
	v_lshlrev_b32_e32 v74, 2, v74
	v_lshl_add_u32 v74, v75, 8, v74
	v_lshl_add_u32 v74, v76, 10, v74
	s_add_i32 s100, s97, 0x0
	v_add_u32_e32 v74, s100, v74
	v_xor_b32_e32 v76, 0, v75
	v_xor_b32_e32 v77, 1, v75
	v_xor_b32_e32 v78, 2, v75
	v_xor_b32_e32 v79, 3, v75
	v_lshl_add_u32 v76, v76, 4, v74
	v_lshl_add_u32 v77, v77, 4, v74
	v_lshl_add_u32 v78, v78, 4, v74
	v_lshl_add_u32 v79, v79, 4, v74
	s_waitcnt lgkmcnt(7)
	v_mov_b32_e32 v104, v80
	v_mul_f32_e32 v105, v104, v81
	v_mul_f32_e32 v106, v105, v82
	v_mul_f32_e32 v107, v106, v83
	v_mul_f32_e32 v108, v107, v84
	v_mul_f32_e32 v109, v108, v85
	v_mul_f32_e32 v110, v109, v86
	v_mul_f32_e32 v111, v110, v87
	v_mov_b32_e32 v112, v88
	v_mul_f32_e32 v113, v104, v89
	v_mul_f32_e32 v114, v105, v90
	v_mul_f32_e32 v115, v106, v91
	v_mul_f32_e32 v116, v107, v92
	v_mul_f32_e32 v117, v108, v93
	v_mul_f32_e32 v118, v109, v94
	v_mul_f32_e32 v119, v110, v95
	v_mul_f32_e32 v120, v104, v96
	s_waitcnt lgkmcnt(0)
	v_mul_f32_e32 v121, v105, v97
	v_mul_f32_e32 v122, v106, v98
	v_mul_f32_e32 v123, v107, v99
	v_mul_f32_e32 v124, v108, v100
	v_mul_f32_e32 v125, v109, v101
	v_mul_f32_e32 v126, v110, v102
	v_mul_f32_e32 v127, v111, v103
	ds_write_b32 v76, v112
	ds_write_b32 v77, v113
	ds_write_b32 v78, v114
	ds_write_b32 v79, v115
	ds_write_b32 v76, v116 offset:64
	ds_write_b32 v77, v117 offset:64
	ds_write_b32 v78, v118 offset:64
	ds_write_b32 v79, v119 offset:64
	ds_write_b32 v76, v120 offset:128
	ds_write_b32 v77, v121 offset:128
	ds_write_b32 v78, v122 offset:128
	ds_write_b32 v79, v123 offset:128
	ds_write_b32 v76, v124 offset:192
	ds_write_b32 v77, v125 offset:192
	ds_write_b32 v78, v126 offset:192
	ds_write_b32 v79, v127 offset:192

.Lmy_ck_drE_h:
	s_waitcnt lgkmcnt(0)
	s_bfe_u32 s96, s62, 0x20006
	s_and_b32 s97, s96, 1
	s_mul_i32 s97, s97, 0x2700
	s_mov_b32 s101, 0x1c000
	s_mov_b32 s100, 0x6100
	s_bitcmp0_b32 s65, 0
	s_cselect_b32 s101, 0xe000, s101
	s_cselect_b32 s100, 0x4e00, s100
	s_cmp_gt_u32 s96, 1
	s_cselect_b32 s100, s100, 0
	s_add_i32 s97, s97, s101
	s_add_i32 s97, s97, s100
	s_mov_b32 s96, s97
	v_and_b32_e32 v72, 3, v233
	v_lshrrev_b32_e32 v73, 2, v233
	v_lshlrev_b32_e32 v72, 2, v72
	v_lshl_add_u32 v72, v73, 8, v72
	v_lshl_add_u32 v72, v234, 6, v72
	s_add_i32 s97, s96, 0x1000
	v_add_u32_e32 v78, s97, v72
	v_xor_b32_e32 v79, v224, v234
	v_lshl_add_u32 v79, v79, 4, s96
	ds_read_b128 v[96:99], v79
	ds_read_b128 v[100:103], v79 offset:1024
	ds_read_b128 v[104:107], v79 offset:2048
	ds_read_b128 v[108:111], v79 offset:3072
	ds_read_b32 v80, v78
	ds_read_b32 v81, v78 offset:16
	ds_read_b32 v82, v78 offset:32
	ds_read_b32 v83, v78 offset:48
	ds_read_b32 v84, v78 offset:1024
	ds_read_b32 v85, v78 offset:1040
	ds_read_b32 v86, v78 offset:1056
	ds_read_b32 v87, v78 offset:1072
	ds_read_b32 v88, v78 offset:2048
	ds_read_b32 v89, v78 offset:2064
	ds_read_b32 v90, v78 offset:2080
	ds_read_b32 v91, v78 offset:2096
	ds_read_b32 v92, v78 offset:3072
	ds_read_b32 v93, v78 offset:3088
	ds_read_b32 v94, v78 offset:3104
	ds_read_b32 v95, v78 offset:3120
	v_lshl_add_u32 v74, v224, 2, s96
	ds_write_b32 v74, v235 offset:9728
	v_add_u32_e32 v75, -1, v233
	v_mov_b32_e32 v76, -1
	v_cndmask_b32_e64 v75, v76, v75, s[98:99]
	v_cmp_lt_u32_e64 s[100:101], 7, v233
	v_add_u32_e32 v76, -8, v233
	v_and_b32_e32 v77, 1, v234
	v_cndmask_b32_e64 v75, v75, v76, s[100:101]
	v_lshlrev_b32_e32 v77, 2, v77
	v_sub_u32_e32 v76, v75, v77
	v_lshlrev_b32_e32 v77, 2, v234
	v_sub_u32_e32 v77, v233, v77
	v_add_u32_e32 v77, -1, v77
	s_waitcnt lgkmcnt(10)
	v_mfma_f32_16x16x4_f32 v[244:247], v80, v96, 0
	v_mfma_f32_16x16x4_f32 v[240:243], v81, v97, 0
	v_mfma_f32_16x16x4_f32 v[244:247], v82, v98, v[244:247]
	v_mfma_f32_16x16x4_f32 v[240:243], v83, v99, v[240:243]
	v_mfma_f32_16x16x4_f32 v[244:247], v84, v100, v[244:247]
	v_mfma_f32_16x16x4_f32 v[240:243], v85, v101, v[240:243]
	v_mfma_f32_16x16x4_f32 v[244:247], v86, v102, v[244:247]
	s_waitcnt lgkmcnt(2)
	v_mfma_f32_16x16x4_f32 v[240:243], v87, v103, v[240:243]
	v_mfma_f32_16x16x4_f32 v[244:247], v88, v104, v[244:247]
	v_mfma_f32_16x16x4_f32 v[240:243], v89, v105, v[240:243]
	v_mfma_f32_16x16x4_f32 v[244:247], v90, v106, v[244:247]
	v_mfma_f32_16x16x4_f32 v[240:243], v91, v107, v[240:243]
	v_mfma_f32_16x16x4_f32 v[244:247], v92, v108, v[244:247]
	v_mfma_f32_16x16x4_f32 v[240:243], v93, v109, v[240:243]
	v_mfma_f32_16x16x4_f32 v[244:247], v94, v110, v[244:247]
	s_waitcnt lgkmcnt(1)
	v_mfma_f32_16x16x4_f32 v[240:243], v95, v111, v[240:243]
	s_nop 9
	v_add_f32_e32 v244, v244, v240
	v_add_f32_e32 v245, v245, v241
	v_add_f32_e32 v246, v246, v242
	v_add_f32_e32 v247, v247, v243
	v_cmp_le_i32_e64 s[96:97], 0, v76
	v_cmp_le_i32_e64 s[100:101], 1, v76
	s_nop 0
	v_cndmask_b32_e64 v128, 0, v244, s[96:97]
	v_cndmask_b32_e64 v129, 0, v245, s[100:101]
	v_cmp_le_i32_e64 s[96:97], 2, v76
	v_cmp_le_i32_e64 s[100:101], 3, v76
	s_nop 0
	v_cndmask_b32_e64 v130, 0, v246, s[96:97]
	v_cndmask_b32_e64 v131, 0, v247, s[100:101]
	s_bfe_u32 s96, s62, 0x20006
	s_and_b32 s97, s96, 1
	s_mul_i32 s97, s97, 0x2700
	s_mov_b32 s101, 0x1c000
	s_mov_b32 s100, 0x6100
	s_bitcmp0_b32 s65, 0
	s_cselect_b32 s101, 0xe000, s101
	s_cselect_b32 s100, 0x4e00, s100
	s_cmp_gt_u32 s96, 1
	s_cselect_b32 s100, s100, 0
	s_add_i32 s97, s97, s101
	s_add_i32 s97, s97, s100
	v_xor_b32_e32 v74, v224, v234
	v_lshl_add_u32 v74, v74, 4, s97
	ds_write_b128 v74, v[128:131] offset:8448
	v_lshlrev_b32_e32 v75, 7, v234
	v_lshl_add_u32 v75, v233, 2, v75
	v_add_u32_e32 v75, s97, v75
	v_cmp_le_i32_e64 s[96:97], 0, v77
	v_cmp_le_i32_e64 s[100:101], 1, v77
	s_nop 0
	v_cndmask_b32_e64 v132, 0, v244, s[96:97]
	v_cndmask_b32_e64 v133, 0, v245, s[100:101]
	v_cmp_le_i32_e64 s[96:97], 2, v77
	v_cmp_le_i32_e64 s[100:101], 3, v77
	s_nop 0
	v_cndmask_b32_e64 v134, 0, v246, s[96:97]
	v_cndmask_b32_e64 v135, 0, v247, s[100:101]
	s_mov_b64 exec, 0x00ff00ff
	ds_write_b32 v75, v132 offset:9472
	ds_write_b32 v75, v133 offset:9504
	ds_write_b32 v75, v134 offset:9536
	ds_write_b32 v75, v135 offset:9568
	s_mov_b64 exec, -1
	s_branch .LBB0_655
